# static s_setprio 1 for waves 4-7 during both attention phases
# baseline (speedup 1.0000x reference)
; #define OPAQUE_IDS int tx = threadIdx.x; int bx = blockIdx.x; asm volatile("" : "+v"(tx), "+s"(bx));
; template <int DQK, int MODE>
; DI void attn_phase(const bf16_t* __restrict__ QK, int ldq, const bf16_t* __restrict__ Vt, int VC, bf16_t* __restrict__ O, int ldo, int nhu, bool skip_ctx, const float* __restrict__ qgain, const f32x2* __restrict__ rope, float qscale, char* shm) {
;     OPAQUE_IDS
;     constexpr int KS = DQK * 2 + 16, VS = 144, KCH = DQK / 8, NKC = 64 * KCH / NTHR;
;     constexpr int BUFB = 64 * KS + 128 * VS;
;     char* Kl = shm; char* Vl = shm + 64 * KS;
;     const int tid = tx, w = tid >> 6, lane = tid & 63, r = lane & 31, h = lane >> 5;
;     const int nlat = NB * nhu * 8, nunits = nlat + (skip_ctx ? 0 : NB * nhu);
;     for (int u = bx; u < nunits; u += gridDim.x) {
;         int qt, hu, b;
;         if (u < nlat) { qt = 1 + (u & 7); hu = (u >> 3) % nhu; b = (u >> 3) / nhu; } else { const int v = u - nlat; qt = 0; hu = v % nhu; b = v / nhu; }
;         const int qoff = hu * DQK, koff = 1024 + (MODE == 0 ? hu * 64 : (hu >> 2) * 128), voff = (MODE == 0 ? (hu >> 1) : (hu >> 2)) * 128, ooff = hu * 128;
;         const int nkt = qt == 0 ? 4 : 36;
;         const size_t qrow = (size_t)b * LT + qt * 256 + w * 32 + r;
.LBB0_1283:
	s_or_b64 exec, exec, s[0:1]
	s_waitcnt lgkmcnt(0)
	v_mov_b32_e32 v0, v252
	s_mov_b32 s7, s87
	s_barrier
	v_readfirstlane_b32 s98, v252
	s_nop 3
	s_lshr_b32 s98, s98, 8
	s_cmp_lg_u32 s98, 0
	s_cbranch_scc0 .Lprio_a1
	s_setprio 1
.Lprio_a1:
	s_cmpk_gt_i32 s7, 0x47f
	s_cbranch_scc1 .LBB0_1330
	v_ashrrev_i32_e32 v2, 1, v0
	v_and_b32_e32 v4, 31, v0
	v_and_b32_e32 v3, 0xffffffe0, v2
	v_ashrrev_i32_e32 v125, 31, v3
	v_or_b32_e32 v124, v3, v4
	v_mbcnt_hi_u32_b32 v3, -1, v253
	s_movk_i32 s0, 0xffe0
	v_and_b32_e32 v6, 64, v3
	v_xor_b32_e32 v5, 32, v3
	v_add_u32_e32 v6, 64, v6
	v_bfi_b32 v2, s0, v2, v0
	v_cmp_lt_i32_e32 vcc, v5, v6
	v_add_u32_e32 v157, 0xffffff00, v2
	v_ashrrev_i32_e32 v2, 31, v0
	v_cndmask_b32_e32 v3, v3, v5, vcc
	v_lshrrev_b32_e32 v2, 29, v2
	v_lshlrev_b32_e32 v127, 2, v3
	v_add_u32_e32 v3, v0, v2
	v_ashrrev_i32_e32 v2, 3, v3
	v_and_b32_e32 v3, -8, v3
	v_sub_u32_e32 v5, v0, v3
	v_ashrrev_i32_e32 v3, 31, v2
	s_movk_i32 s4, 0x90
	v_bfe_u32 v1, v0, 5, 1
	v_lshlrev_b64 v[132:133], 12, v[2:3]
	v_lshlrev_b32_e32 v134, 3, v5
	v_mul_lo_u32 v2, v2, s4
	v_lshlrev_b32_e32 v5, 4, v5
	v_mov_b32_e32 v129, 0
	v_lshlrev_b32_e32 v128, 6, v1
	v_lshlrev_b32_e32 v3, 3, v0
	v_add3_u32 v158, 0, v2, v5
	v_lshlrev_b32_e32 v2, 4, v0
	v_lshl_add_u64 v[130:131], s[10:11], 0, v[128:129]
	v_and_b32_e32 v5, 0x60, v2
	v_and_b32_e32 v3, 8, v3
	v_and_b32_e32 v128, 0x70, v2
	v_ashrrev_i32_e32 v2, 3, v0
	s_movk_i32 s5, 0x1200
	v_add_u32_e32 v0, 0x200, v0
	v_lshlrev_b32_e32 v126, 3, v1
	v_add3_u32 v159, 0, v5, v3
	v_mul_u32_u24_e32 v3, 0x90, v4
	v_lshlrev_b32_e32 v1, 4, v1
	v_mad_i64_i32 v[138:139], s[0:1], v2, s5, 0
	v_ashrrev_i32_e32 v0, 3, v0
	v_mad_i64_i32 v[140:141], s[0:1], v0, s5, 0
	v_mul_lo_u32 v161, v0, s4
	v_add3_u32 v162, 0, v3, v1
	v_add3_u32 v163, 0, v1, v3
	v_or_b32_e32 v0, v138, v128
	v_mov_b32_e32 v1, v139
	v_lshl_add_u64 v[0:1], s[68:69], 0, v[0:1]
	s_mov_b64 s[0:1], 0x92da080
	v_lshl_add_u64 v[142:143], v[0:1], 0, s[0:1]
	v_or_b32_e32 v0, v140, v128
	v_mov_b32_e32 v1, v141
	v_ashrrev_i32_e32 v135, 31, v134
	v_lshl_add_u64 v[0:1], s[68:69], 0, v[0:1]
	v_lshl_add_u64 v[144:145], v[0:1], 0, s[0:1]
	v_lshl_add_u64 v[0:1], v[134:135], 1, v[132:133]
	s_add_u32 s2, s68, 0xb6da000
	v_lshl_add_u64 v[0:1], s[68:69], 0, v[0:1]
	s_mov_b64 s[0:1], 0x4b1a800
	s_addc_u32 s3, s69, 0
	v_lshl_add_u64 v[136:137], s[8:9], 0, v[128:129]
	v_mul_lo_u32 v160, v2, s4
	v_lshl_add_u64 v[146:147], v[0:1], 0, s[0:1]
	v_mov_b32_e32 v164, 0x358637bd
	s_mov_b32 s30, 0x800000
	s_mov_b64 s[4:5], 0x80
	s_mov_b64 s[8:9], 0x40000
	v_lshlrev_b32_e32 v128, 1, v126
	v_mov_b32_e32 v165, 0x1200
	s_branch .LBB0_1288

; DI unsigned xb_add(unsigned* p, unsigned v) { return __hip_atomic_fetch_add(p, v, __ATOMIC_RELAXED, __HIP_MEMORY_SCOPE_AGENT); }
; template <int DQK, int MODE>
; DI void attn_phase(const bf16_t* __restrict__ QK, int ldq, const bf16_t* __restrict__ Vt, int VC, bf16_t* __restrict__ O, int ldo, int nhu, bool skip_ctx, const float* __restrict__ qgain, const f32x2* __restrict__ rope, float qscale, char* shm) {
;     ...
;     __syncthreads();
; DI void xcd_barrier(const XcdBarrier& b) {
;     asm volatile("s_waitcnt vmcnt(0)" ::: "memory");
;     __syncthreads();
;     if (threadIdx.x == 0) {
;         unsigned* bar = b.bar;
;         __builtin_amdgcn_s_waitcnt(0);
;         unsigned nloc = b.st[0], nx = b.st[1];
;         if (nloc == 0u) { xcd_barrier_complete(bar, b.x, nloc, nx); b.st[0] = nloc; b.st[1] = nx; }
;         const unsigned old = xb_add(&bar[XB_XSUB(b.x)], 1u);
.LBB0_1330:
	s_setprio 0
	s_barrier
	s_waitcnt vmcnt(0)
	s_barrier
	s_mov_b64 s[0:1], exec
	v_readlane_b32 s2, v254, 5
	v_readlane_b32 s3, v254, 6
	s_and_b64 s[2:3], s[0:1], s[2:3]
	s_mov_b64 exec, s[2:3]
	s_cbranch_execz .LBB0_1382
	s_add_i32 s2, 0, 0x20000
	v_mov_b32_e32 v0, s2
	s_waitcnt vmcnt(0) expcnt(0) lgkmcnt(0)
	ds_read_b32 v2, v0
	s_add_i32 s2, 0, 0x20004
	v_mov_b32_e32 v0, s2
	ds_read_b32 v0, v0
	s_waitcnt lgkmcnt(1)
	v_cmp_ne_u32_e32 vcc, 0, v2
	s_cbranch_vccnz .LBB0_1346
	v_readlane_b32 s8, v254, 1
	v_readlane_b32 s9, v254, 2
	s_load_dword s4, s[8:9], 0x14
	s_load_dwordx2 s[2:3], s[8:9], 0x4
	s_mov_b32 s71, 1
	v_mov_b32_e32 v16, 0
	s_waitcnt lgkmcnt(0)
	s_lshr_b32 s7, s4, 16
	s_and_b32 s4, s4, 0xffff
	s_cmp_lg_u32 s4, 0
	s_cselect_b64 s[4:5], -1, 0
	s_cmp_lg_u64 s[4:5], 0
	s_addc_u32 s2, s2, 0
	s_cmp_lg_u32 s7, 0
	s_cselect_b64 s[4:5], -1, 0
	s_cmp_lg_u64 s[4:5], 0
	s_mul_i32 s2, s2, s26
	s_addc_u32 s3, s3, 0
	s_mul_i32 s7, s2, s3
	s_add_u32 s2, s68, 0x16ada200
	s_addc_u32 s3, s69, 0
	s_add_u32 s4, s68, 0x16ada400
	s_addc_u32 s5, s69, 0
	s_add_u32 s8, s68, 0x16ada500
	s_addc_u32 s9, s69, 0
	s_add_u32 s10, s68, 0x16ada600
	s_addc_u32 s11, s69, 0
	s_add_u32 s12, s68, 0x16ada700
	s_addc_u32 s13, s69, 0
	s_add_u32 s14, s68, 0x16ada800
	s_addc_u32 s15, s69, 0
	s_add_u32 s30, s68, 0x16ada900
	s_addc_u32 s31, s69, 0
	s_add_u32 s34, s68, 0x16adaa00
	s_addc_u32 s35, s69, 0
	s_add_u32 s36, s68, 0x16adab00
	s_addc_u32 s37, s69, 0
	s_add_u32 s38, s68, 0x16adac00
	s_addc_u32 s39, s69, 0
	s_add_u32 s40, s68, 0x16adad00
	s_addc_u32 s41, s69, 0
	s_add_u32 s42, s68, 0x16adae00
	s_addc_u32 s43, s69, 0
	s_add_u32 s44, s68, 0x16adaf00
	s_addc_u32 s45, s69, 0
	s_add_u32 s46, s68, 0x16adb000
	s_addc_u32 s47, s69, 0
	s_add_u32 s48, s68, 0x16adb100
	s_addc_u32 s49, s69, 0
	s_add_u32 s50, s68, 0x16adb200
	s_addc_u32 s51, s69, 0
	s_add_u32 s52, s68, 0x16adb300
	s_addc_u32 s53, s69, 0
	s_branch .LBB0_1334

; #define OPAQUE_IDS int tx = threadIdx.x; int bx = blockIdx.x; asm volatile("" : "+v"(tx), "+s"(bx));
; template <int DQK, int MODE>
; DI void attn_phase(const bf16_t* __restrict__ QK, int ldq, const bf16_t* __restrict__ Vt, int VC, bf16_t* __restrict__ O, int ldo, int nhu, bool skip_ctx, const float* __restrict__ qgain, const f32x2* __restrict__ rope, float qscale, char* shm) {
;     OPAQUE_IDS
;     constexpr int KS = DQK * 2 + 16, VS = 144, KCH = DQK / 8, NKC = 64 * KCH / NTHR;
;     constexpr int BUFB = 64 * KS + 128 * VS;
;     char* Kl = shm; char* Vl = shm + 64 * KS;
;     const int tid = tx, w = tid >> 6, lane = tid & 63, r = lane & 31, h = lane >> 5;
;     const int nlat = NB * nhu * 8, nunits = nlat + (skip_ctx ? 0 : NB * nhu);
;     for (int u = bx; u < nunits; u += gridDim.x) {
;         int qt, hu, b;
;         if (u < nlat) { qt = 1 + (u & 7); hu = (u >> 3) % nhu; b = (u >> 3) / nhu; } else { const int v = u - nlat; qt = 0; hu = v % nhu; b = v / nhu; }
;         const int qoff = hu * DQK, koff = 1024 + (MODE == 0 ? hu * 64 : (hu >> 2) * 128), voff = (MODE == 0 ? (hu >> 1) : (hu >> 2)) * 128, ooff = hu * 128;
;         const int nkt = qt == 0 ? 4 : 36;
;         const size_t qrow = (size_t)b * LT + qt * 256 + w * 32 + r;
.LBB0_3387:
	s_or_b64 exec, exec, s[0:1]
	s_waitcnt lgkmcnt(0)
	v_mov_b32_e32 v0, v252
	s_mov_b32 s14, s87
	s_barrier
	v_readfirstlane_b32 s98, v252
	s_nop 3
	s_lshr_b32 s98, s98, 8
	s_cmp_lg_u32 s98, 0
	s_cbranch_scc0 .Lprio_a3
	s_setprio 1
.Lprio_a3:
	s_cmpk_gt_i32 s14, 0x1ff
	s_cbranch_scc1 .LBB0_3397
	v_ashrrev_i32_e32 v3, 1, v0
	v_and_b32_e32 v2, 31, v0
	v_and_b32_e32 v4, 0xffffffe0, v3
	v_ashrrev_i32_e32 v145, 31, v4
	v_or_b32_e32 v144, v4, v2
	v_mbcnt_hi_u32_b32 v4, -1, v253
	v_and_b32_e32 v6, 64, v4
	v_xor_b32_e32 v5, 32, v4
	v_add_u32_e32 v6, 64, v6
	v_cmp_lt_i32_e32 vcc, v5, v6
	s_movk_i32 s0, 0xffe0
	v_bfi_b32 v187, s0, v3, v0
	v_cndmask_b32_e32 v4, v4, v5, vcc
	v_lshlrev_b32_e32 v147, 2, v4
	v_lshlrev_b32_e32 v3, 3, v0
	v_lshlrev_b32_e32 v4, 4, v0
	v_bfe_u32 v1, v0, 5, 1
	v_and_b32_e32 v5, 0x60, v4
	v_and_b32_e32 v3, 8, v3
	v_lshlrev_b32_e32 v146, 3, v1
	v_lshlrev_b32_e32 v148, 6, v1
	v_add3_u32 v188, 0, v5, v3
	v_lshl_add_u32 v3, v1, 4, 0
	v_ashrrev_i32_e32 v1, 31, v0
	v_add_u32_e32 v6, 0x200, v0
	v_lshrrev_b32_e32 v1, 28, v1
	v_ashrrev_i32_e32 v7, 31, v6
	v_add_u32_e32 v1, v0, v1
	v_lshrrev_b32_e32 v7, 28, v7
	v_mov_b32_e32 v149, 0
	v_ashrrev_i32_e32 v5, 4, v1
	v_and_b32_e32 v1, -16, v1
	v_add_u32_e32 v7, v6, v7
	v_lshl_add_u64 v[150:151], s[8:9], 0, v[148:149]
	v_sub_u32_e32 v1, v0, v1
	s_movk_i32 s15, 0xa00
	v_ashrrev_i32_e32 v8, 4, v7
	v_and_b32_e32 v148, 0x70, v4
	v_ashrrev_i32_e32 v0, 3, v0
	s_movk_i32 s0, 0x1200
	v_ashrrev_i32_e32 v4, 3, v6
	v_mad_i64_i32 v[152:153], s[2:3], v5, s15, 0
	v_mad_i64_i32 v[156:157], s[2:3], v8, s15, 0
	v_mad_i64_i32 v[162:163], s[2:3], v0, s0, 0
	v_mad_i64_i32 v[164:165], s[2:3], v4, s0, 0
	v_and_b32_e32 v7, -16, v7
	s_movk_i32 s2, 0x90
	v_sub_u32_e32 v7, v6, v7
	v_mul_lo_u32 v193, v0, s2
	v_mov_b32_e32 v0, 0x3600
	v_lshlrev_b32_e32 v154, 3, v1
	v_lshlrev_b32_e32 v158, 3, v7
	v_lshlrev_b32_e32 v190, 4, v1
	v_mul_lo_u32 v194, v4, s2
	v_mad_u32_u24 v4, v2, s2, v0
	v_mad_u32_u24 v196, v2, s2, v3
	v_or_b32_e32 v0, v162, v148
	v_mov_b32_e32 v1, v163
	s_mov_b64 s[2:3], 0x77da080
	v_ashrrev_i32_e32 v159, 31, v158
	v_lshl_add_u64 v[166:167], v[0:1], 0, s[2:3]
	v_or_b32_e32 v0, v164, v148
	v_mov_b32_e32 v1, v165
	v_lshl_add_u64 v[168:169], v[0:1], 0, s[2:3]
	v_lshlrev_b64 v[0:1], 1, v[158:159]
	v_mad_i64_i32 v[0:1], s[2:3], v8, s15, v[0:1]
	v_ashrrev_i32_e32 v155, 31, v154
	s_movk_i32 s0, 0x110
	s_mov_b64 s[2:3], 0x4b02800
	v_mul_lo_u32 v189, v5, s0
	v_mul_lo_u32 v191, v8, s0
	v_lshl_add_u64 v[170:171], v[0:1], 0, s[2:3]
	v_lshlrev_b64 v[0:1], 1, v[154:155]
	v_add_u32_e32 v6, 0, v189
	v_add_u32_e32 v9, 0, v191
	v_lshlrev_b32_e32 v192, 4, v7
	v_mad_i64_i32 v[0:1], s[4:5], v5, s15, v[0:1]
	s_mov_b32 s1, 0
	v_lshl_add_u64 v[160:161], s[6:7], 0, v[148:149]
	v_mad_u32_u24 v195, v2, s0, v3
	v_lshl_add_u64 v[172:173], v[0:1], 0, s[2:3]
	v_mov_b32_e32 v197, 0x358637bd
	s_mov_b32 s24, 0x800000
	v_add_u32_e32 v198, v6, v190
	v_add_u32_e32 v199, v9, v192
	s_mov_b64 s[2:3], 0x80
	s_mov_b64 s[4:5], 0x28000
	v_add_u32_e32 v200, v3, v4
	v_mov_b32_e32 v201, 0x900
	v_mov_b32_e32 v202, 0x1200
	v_mov_b32_e32 v203, 0x120000
	s_branch .LBB0_3392

; DI unsigned xb_add(unsigned* p, unsigned v) { return __hip_atomic_fetch_add(p, v, __ATOMIC_RELAXED, __HIP_MEMORY_SCOPE_AGENT); }
; template <int DQK, int MODE>
; DI void attn_phase(const bf16_t* __restrict__ QK, int ldq, const bf16_t* __restrict__ Vt, int VC, bf16_t* __restrict__ O, int ldo, int nhu, bool skip_ctx, const float* __restrict__ qgain, const f32x2* __restrict__ rope, float qscale, char* shm) {
;     ...
;     __syncthreads();
; DI void xcd_barrier(const XcdBarrier& b) {
;     asm volatile("s_waitcnt vmcnt(0)" ::: "memory");
;     __syncthreads();
;     if (threadIdx.x == 0) {
;         unsigned* bar = b.bar;
;         __builtin_amdgcn_s_waitcnt(0);
;         unsigned nloc = b.st[0], nx = b.st[1];
;         if (nloc == 0u) { xcd_barrier_complete(bar, b.x, nloc, nx); b.st[0] = nloc; b.st[1] = nx; }
;         const unsigned old = xb_add(&bar[XB_XSUB(b.x)], 1u);
.LBB0_3397:
	s_setprio 0
	s_barrier
	s_waitcnt vmcnt(0)
	s_barrier
	s_mov_b64 s[0:1], exec
	v_readlane_b32 s2, v254, 5
	v_readlane_b32 s3, v254, 6
	s_and_b64 s[2:3], s[0:1], s[2:3]
	s_mov_b64 exec, s[2:3]
	s_cbranch_execz .LBB0_3449
	s_add_i32 s2, 0, 0x20000
	v_mov_b32_e32 v0, s2
	s_waitcnt vmcnt(0) expcnt(0) lgkmcnt(0)
	ds_read_b32 v2, v0
	s_add_i32 s2, 0, 0x20004
	v_mov_b32_e32 v0, s2
	ds_read_b32 v0, v0
	s_waitcnt lgkmcnt(1)
	v_cmp_ne_u32_e32 vcc, 0, v2
	s_cbranch_vccnz .LBB0_3413
	v_readlane_b32 s6, v254, 1
	v_readlane_b32 s7, v254, 2
	s_load_dword s4, s[6:7], 0x14
	s_load_dwordx2 s[2:3], s[6:7], 0x4
	s_mov_b32 s57, 1
	v_mov_b32_e32 v16, 0
	s_waitcnt lgkmcnt(0)
	s_lshr_b32 s6, s4, 16
	s_and_b32 s4, s4, 0xffff
	s_cmp_lg_u32 s4, 0
	s_cselect_b64 s[4:5], -1, 0
	s_cmp_lg_u64 s[4:5], 0
	s_addc_u32 s2, s2, 0
	s_cmp_lg_u32 s6, 0
	s_cselect_b64 s[4:5], -1, 0
	s_cmp_lg_u64 s[4:5], 0
	s_mul_i32 s56, s2, s26
	s_addc_u32 s2, s3, 0
	s_mul_i32 s56, s56, s2
	s_add_u32 s2, s68, 0x16ada200
	s_addc_u32 s3, s69, 0
	s_add_u32 s4, s68, 0x16ada400
	s_addc_u32 s5, s69, 0
	s_add_u32 s6, s68, 0x16ada500
	s_addc_u32 s7, s69, 0
	s_add_u32 s8, s68, 0x16ada600
	s_addc_u32 s9, s69, 0
	s_add_u32 s10, s68, 0x16ada700
	s_addc_u32 s11, s69, 0
	s_add_u32 s12, s68, 0x16ada800
	s_addc_u32 s13, s69, 0
	s_add_u32 s14, s68, 0x16ada900
	s_addc_u32 s15, s69, 0
	s_add_u32 s24, s68, 0x16adaa00
	s_addc_u32 s25, s69, 0
	s_add_u32 s30, s68, 0x16adab00
	s_addc_u32 s31, s69, 0
	s_add_u32 s34, s68, 0x16adac00
	s_addc_u32 s35, s69, 0
	s_add_u32 s36, s68, 0x16adad00
	s_addc_u32 s37, s69, 0
	s_add_u32 s38, s68, 0x16adae00
	s_addc_u32 s39, s69, 0
	s_add_u32 s40, s68, 0x16adaf00
	s_addc_u32 s41, s69, 0
	s_add_u32 s42, s68, 0x16adb000
	s_addc_u32 s43, s69, 0
	s_add_u32 s44, s68, 0x16adb100
	s_addc_u32 s45, s69, 0
	s_add_u32 s46, s68, 0x16adb200
	s_addc_u32 s47, s69, 0
	s_add_u32 s48, s68, 0x16adb300
	s_addc_u32 s49, s69, 0
	s_branch .LBB0_3401
